# stick-breaking attention epilogue: the 8 out-norm weight loads of an item issued together instead of load-wait-store chains
# speedup vs baseline: 1.2140x; 1.0016x over previous
; DI void phase_sbattn(const Params& p, int wid, int nw) {
;     ...
;     float ss = 0.f;
; #pragma unroll
;     for (int i = 0; i < 16; i++) ss += o0[i] * o0[i] + o1[i] * o1[i];
;     ss += __shfl_xor(ss, 32);
;     const float rstd = rsqrtf(ss * (1.f / 64.f) + EPSF);
;     const int b = bh >> 3, hh = bh & 7;
;     u16* dst = p.mix + (size_t)(b * SEQ + qidx) * 1024 + hh * 64;
;     const float* nw = p.sbo_w + hh * 64;
; #pragma unroll
;     for (int mt = 0; mt < 2; mt++)
; #pragma unroll
;       for (int gg = 0; gg < 4; gg++) {
;         const int d = mt * 32 + 8 * gg + 4 * hf;
;         float4 ww = *(const float4*)(nw + d);
;         float a0, a1, a2, a3;
;         if (mt == 0) { a0 = o0[4 * gg]; a1 = o0[4 * gg + 1]; a2 = o0[4 * gg + 2]; a3 = o0[4 * gg + 3]; }
;         else { a0 = o1[4 * gg]; a1 = o1[4 * gg + 1]; a2 = o1[4 * gg + 2]; a3 = o1[4 * gg + 3]; }
;         u32x2 pk; pk.x = pack2(a0 * rstd * ww.x, a1 * rstd * ww.y); pk.y = pack2(a2 * rstd * ww.z, a3 * rstd * ww.w);
;         *(u32x2*)(dst + d) = pk;
;       }
.LBB0_787:
	s_or_b64 exec, exec, s[74:75]
	v_lshlrev_b32_e32 v34, 2, v103
	s_movk_i32 s0, 0xe000
	v_and_or_b32 v34, v34, s0, v113
	v_ashrrev_i32_e32 v35, 31, v34
	v_readlane_b32 s4, v253, 0
	v_lshlrev_b32_e32 v36, 6, v116
	v_lshlrev_b64 v[34:35], 11, v[34:35]
	v_readlane_b32 s6, v253, 2
	v_readlane_b32 s7, v253, 3
	v_and_b32_e32 v36, 0x1c0, v36
	v_lshlrev_b32_e32 v100, 1, v36
	v_lshl_add_u64 v[34:35], s[6:7], 0, v[34:35]
	v_lshl_add_u64 v[38:39], v[34:35], 0, v[100:101]
	v_lshlrev_b32_e32 v100, 2, v36
	v_lshl_add_u64 v[40:41], v[110:111], 0, v[100:101]
	global_load_dwordx4 v[34:37], v[40:41], off
	global_load_dwordx4 v[60:63], v[40:41], off offset:32
	global_load_dwordx4 v[64:67], v[40:41], off offset:64
	global_load_dwordx4 v[68:71], v[40:41], off offset:96
	global_load_dwordx4 v[72:75], v[40:41], off offset:128
	global_load_dwordx4 v[76:79], v[40:41], off offset:160
	global_load_dwordx4 v[80:83], v[40:41], off offset:192
	global_load_dwordx4 v[84:87], v[40:41], off offset:224
	v_mul_f32_e32 v52, v2, v2
	v_mul_f32_e32 v53, v3, v3
	v_mul_f32_e32 v54, v4, v4
	v_fmac_f32_e32 v52, v18, v18
	v_fmac_f32_e32 v53, v19, v19
	v_mul_f32_e32 v55, v5, v5
	v_fmac_f32_e32 v54, v20, v20
	v_add_f32_e32 v52, v52, v53
	v_mul_f32_e32 v56, v6, v6
	v_fmac_f32_e32 v55, v21, v21
	v_add_f32_e32 v52, v54, v52
	v_mul_f32_e32 v57, v7, v7
	v_fmac_f32_e32 v56, v22, v22
	v_add_f32_e32 v52, v55, v52
	v_pk_mul_f32 v[42:43], v[8:9], v[8:9]
	v_fmac_f32_e32 v57, v23, v23
	v_add_f32_e32 v52, v56, v52
	v_pk_fma_f32 v[42:43], v[24:25], v[24:25], v[42:43]
	v_add_f32_e32 v52, v57, v52
	v_pk_mul_f32 v[44:45], v[10:11], v[10:11]
	v_add_f32_e32 v42, v42, v52
	v_pk_fma_f32 v[44:45], v[26:27], v[26:27], v[44:45]
	v_add_f32_e32 v42, v43, v42
	v_pk_mul_f32 v[46:47], v[12:13], v[12:13]
	v_add_f32_e32 v42, v44, v42
	v_pk_fma_f32 v[46:47], v[28:29], v[28:29], v[46:47]
	v_add_f32_e32 v42, v45, v42
	v_pk_mul_f32 v[48:49], v[14:15], v[14:15]
	v_add_f32_e32 v42, v46, v42
	v_pk_fma_f32 v[48:49], v[30:31], v[30:31], v[48:49]
	v_add_f32_e32 v42, v47, v42
	v_pk_mul_f32 v[50:51], v[16:17], v[16:17]
	v_add_f32_e32 v42, v48, v42
	v_pk_fma_f32 v[50:51], v[32:33], v[32:33], v[50:51]
	v_add_f32_e32 v42, v49, v42
	v_add_f32_e32 v42, v50, v42
	v_add_f32_e32 v42, v51, v42
	ds_bpermute_b32 v43, v148, v42
	v_mov_b32_e32 v113, v101
	v_lshl_add_u64 v[38:39], v[38:39], 0, v[112:113]
	v_add_u32_e32 v103, s33, v103
	v_subrev_u16_e32 v150, s33, v150
	s_waitcnt lgkmcnt(0)
	v_add_f32_e32 v42, v42, v43
	v_fmamk_f32 v42, v42, 0x3c800000, v151
	v_mul_f32_e32 v43, 0x4b800000, v42
	v_cmp_gt_f32_e64 s[0:1], s79, v42
	v_readlane_b32 s5, v253, 1
	v_readlane_b32 s8, v253, 4
	v_cndmask_b32_e64 v42, v42, v43, s[0:1]
	v_rsq_f32_e32 v42, v42
	v_readlane_b32 s9, v253, 5
	v_readlane_b32 s10, v253, 6
	v_readlane_b32 s11, v253, 7
	v_mul_f32_e32 v43, 0x45800000, v42
	v_cndmask_b32_e64 v42, v42, v43, s[0:1]
	v_pk_mul_f32 v[18:19], v[18:19], v[42:43] op_sel_hi:[1,0]
	v_pk_mul_f32 v[20:21], v[20:21], v[42:43] op_sel_hi:[1,0]
	v_pk_mul_f32 v[22:23], v[22:23], v[42:43] op_sel_hi:[1,0]
	v_pk_mul_f32 v[24:25], v[24:25], v[42:43] op_sel_hi:[1,0]
	v_pk_mul_f32 v[2:3], v[2:3], v[42:43] op_sel_hi:[1,0]
	v_pk_mul_f32 v[4:5], v[4:5], v[42:43] op_sel_hi:[1,0]
	v_pk_mul_f32 v[6:7], v[6:7], v[42:43] op_sel_hi:[1,0]
	v_pk_mul_f32 v[8:9], v[8:9], v[42:43] op_sel_hi:[1,0]
	s_movk_i32 s0, 0xfff
	v_cmp_lt_i32_e64 s[0:1], s0, v103
	s_or_b64 s[48:49], s[0:1], s[48:49]
	s_waitcnt vmcnt(0)
	v_pk_mul_f32 v[18:19], v[34:35], v[18:19]
	v_pk_mul_f32 v[20:21], v[36:37], v[20:21]
	v_cvt_pk_bf16_f32 v18, v18, v19
	v_cvt_pk_bf16_f32 v19, v20, v21
	global_store_dwordx2 v[38:39], v[18:19], off
	v_pk_mul_f32 v[18:19], v[60:61], v[22:23]
	v_pk_mul_f32 v[20:21], v[62:63], v[24:25]
	v_cvt_pk_bf16_f32 v18, v18, v19
	v_cvt_pk_bf16_f32 v19, v20, v21
	global_store_dwordx2 v[38:39], v[18:19], off offset:16
	v_pk_mul_f32 v[22:23], v[26:27], v[42:43] op_sel_hi:[1,0]
	v_pk_mul_f32 v[24:25], v[28:29], v[42:43] op_sel_hi:[1,0]
	v_pk_mul_f32 v[18:19], v[22:23], v[64:65]
	v_pk_mul_f32 v[20:21], v[24:25], v[66:67]
	v_cvt_pk_bf16_f32 v18, v18, v19
	v_cvt_pk_bf16_f32 v19, v20, v21
	global_store_dwordx2 v[38:39], v[18:19], off offset:32
	v_pk_mul_f32 v[22:23], v[30:31], v[42:43] op_sel_hi:[1,0]
	v_pk_mul_f32 v[24:25], v[32:33], v[42:43] op_sel_hi:[1,0]
	v_pk_mul_f32 v[18:19], v[22:23], v[68:69]
	v_pk_mul_f32 v[20:21], v[24:25], v[70:71]
	v_cvt_pk_bf16_f32 v18, v18, v19
	v_cvt_pk_bf16_f32 v19, v20, v21
	global_store_dwordx2 v[38:39], v[18:19], off offset:48
	v_pk_mul_f32 v[2:3], v[2:3], v[72:73]
	v_pk_mul_f32 v[4:5], v[4:5], v[74:75]
	v_cvt_pk_bf16_f32 v2, v2, v3
	v_cvt_pk_bf16_f32 v3, v4, v5
	global_store_dwordx2 v[38:39], v[2:3], off offset:64
	v_pk_mul_f32 v[2:3], v[6:7], v[76:77]
	v_pk_mul_f32 v[4:5], v[8:9], v[78:79]
	v_cvt_pk_bf16_f32 v2, v2, v3
	v_cvt_pk_bf16_f32 v3, v4, v5
	global_store_dwordx2 v[38:39], v[2:3], off offset:80
	v_pk_mul_f32 v[6:7], v[10:11], v[42:43] op_sel_hi:[1,0]
	v_pk_mul_f32 v[8:9], v[12:13], v[42:43] op_sel_hi:[1,0]
	v_pk_mul_f32 v[2:3], v[6:7], v[80:81]
	v_pk_mul_f32 v[4:5], v[8:9], v[82:83]
	v_cvt_pk_bf16_f32 v2, v2, v3
	v_cvt_pk_bf16_f32 v3, v4, v5
	global_store_dwordx2 v[38:39], v[2:3], off offset:96
	v_pk_mul_f32 v[6:7], v[14:15], v[42:43] op_sel_hi:[1,0]
	v_pk_mul_f32 v[8:9], v[16:17], v[42:43] op_sel_hi:[1,0]
	v_pk_mul_f32 v[2:3], v[6:7], v[84:85]
	v_pk_mul_f32 v[4:5], v[8:9], v[86:87]
	v_cvt_pk_bf16_f32 v2, v2, v3
	v_cvt_pk_bf16_f32 v3, v4, v5
	global_store_dwordx2 v[38:39], v[2:3], off offset:112
	s_andn2_b64 exec, exec, s[48:49]
	s_cbranch_execz .LBB0_830
